# v29
# speedup vs baseline: 1.0018x; 1.0008x over previous
; #define WAIT_V(n) asm volatile("s_waitcnt vmcnt(" #n ")" ::: "memory")
; #define BAR __builtin_amdgcn_s_barrier()
; __device__ __forceinline__ void gemm_kloop(const u16* __restrict__ A, const u16* __restrict__ Bt, const int K,
;                                            const int brow, const int bcol, f32x4 (&acc)[2][2][4][2], u16* shm, const int tidk,
;                                            const bool first) {
;     ...
;   if (wr == 1) BAR;
;   if (first) WAIT_V(0); else WAIT_V(16);
;   BAR;
.LBB0_149:
	s_or_b64 exec, exec, s[10:11]
	s_cmp_lg_u32 s74, 0
	s_cbranch_scc0 .LBB0_182
	s_waitcnt vmcnt(32)
	s_mov_b32 s90, s70
	s_mov_b32 s9, s58
	s_cbranch_execnz .LBB0_152

; __device__ __forceinline__ void gemm_phase(const Params& P, const int ph, char* smem, const int tid) {
;     ...
;     if (do_rinv) {
;       const float s_ = (rq0.x + rq0.y + rq0.z + rq0.w) + (rq1.x + rq1.y + rq1.z + rq1.w) + (rq2.x + rq2.y + rq2.z + rq2.w) + (rq3.x + rq3.y + rq3.z + rq3.w);
;       rinv_all[((tcount + 1) & 1) * 256 + tid] = rsqrtf(s_ * (1.f / 1024.f) + EPS);
;     }
.LBB0_253:
	s_waitcnt vmcnt(40)
	v_mov_b32_e32 v4, v27
	s_waitcnt vmcnt(40)
	v_mov_b32_e32 v5, v31
	v_mov_b32_e32 v27, v30
	v_mov_b32_e32 v2, v29
	v_mov_b32_e32 v29, v32
	v_pk_add_f32 v[4:5], v[26:27], v[4:5]
	v_mov_b32_e32 v3, v33
	v_mov_b32_e32 v8, v19
	v_mov_b32_e32 v9, v23
	v_mov_b32_e32 v19, v22
	v_pk_add_f32 v[4:5], v[4:5], v[28:29]
	v_mov_b32_e32 v6, v21
	v_mov_b32_e32 v21, v24
	v_pk_add_f32 v[2:3], v[4:5], v[2:3]
	v_pk_add_f32 v[4:5], v[18:19], v[8:9]
	v_mov_b32_e32 v7, v25
	v_pk_add_f32 v[4:5], v[4:5], v[20:21]
	v_add_f32_e32 v0, v2, v3
	v_pk_add_f32 v[4:5], v[4:5], v[6:7]
	s_xor_b32 s0, s88, 0x100
	v_add_f32_e32 v0, v5, v0
	v_add_f32_e32 v0, v4, v0
	v_fmamk_f32 v0, v0, 0x3a800000, v193
	v_mul_f32_e32 v2, 0x4b800000, v0
	v_cmp_gt_f32_e32 vcc, s68, v0
	s_nop 1
	v_cndmask_b32_e32 v0, v0, v2, vcc
	v_rsq_f32_e32 v0, v0
	s_nop 0
	v_mul_f32_e32 v2, 0x45800000, v0
	v_cndmask_b32_e32 v0, v0, v2, vcc
	v_lshl_add_u32 v2, s0, 2, v188
	ds_write_b32 v2, v0
	s_branch .LBB0_146
